# v18 = v17 + first grid-barrier census: 16 serialized counter loads issued together with one wait
# baseline (speedup 1.0000x reference)
; __device__ __forceinline__ unsigned xb_ld(unsigned* p)              { return __hip_atomic_load(p, __ATOMIC_RELAXED, __HIP_MEMORY_SCOPE_AGENT); }
; __device__ __forceinline__ void xcd_barrier_complete(unsigned* bar, unsigned x, unsigned& nloc, unsigned& nx) {
;     ...
;     for (;;) {
;         sum = 0u; cnt = 0u; mine = 0u;
; #pragma unroll
;         for (unsigned j = 0; j < 16; ++j) { const unsigned c = xb_ld(&bar[XB_XCNT(j)]); sum += c; cnt += (c > 0u) ? 1u : 0u; mine = (j == x) ? c : mine; }
;         if (sum == G) break;
.LBB0_213:
	s_waitcnt lgkmcnt(0)
	v_mov_b64_e32 v[20:21], s[36:37]
	v_mov_b64_e32 v[22:23], s[0:1]
	v_mov_b64_e32 v[24:25], s[4:5]
	v_mov_b64_e32 v[26:27], s[6:7]
	v_mov_b64_e32 v[28:29], s[8:9]
	flat_load_dword v1, v[20:21] offset:1024 sc1
	flat_load_dword v0, v[20:21] offset:1280 sc1
	flat_load_dword v2, v[20:21] offset:1536 sc1
	flat_load_dword v3, v[20:21] offset:1792 sc1
	flat_load_dword v4, v[20:21] offset:2048 sc1
	flat_load_dword v5, v[20:21] offset:2304 sc1
	flat_load_dword v6, v[20:21] offset:2560 sc1
	flat_load_dword v7, v[20:21] offset:2816 sc1
	flat_load_dword v8, v[20:21] offset:3072 sc1
	flat_load_dword v9, v[20:21] offset:3328 sc1
	flat_load_dword v10, v[20:21] offset:3584 sc1
	flat_load_dword v11, v[20:21] offset:3840 sc1
	flat_load_dword v12, v[22:23] sc1
	flat_load_dword v13, v[24:25] sc1
	flat_load_dword v14, v[26:27] sc1
	flat_load_dword v15, v[28:29] sc1
	s_or_b64 s[16:17], s[16:17], exec
	s_or_b64 s[14:15], s[14:15], exec
	s_waitcnt vmcnt(0) lgkmcnt(0)
	v_add_u32_e32 v16, v0, v1
	v_add_u32_e32 v16, v16, v2
	v_add_u32_e32 v16, v16, v3
	v_add_u32_e32 v16, v16, v4
	v_add_u32_e32 v16, v16, v5
	v_add_u32_e32 v16, v16, v6
	v_add_u32_e32 v16, v16, v7
	v_add_u32_e32 v16, v16, v8
	v_add_u32_e32 v16, v16, v9
	v_add_u32_e32 v16, v16, v10
	v_add_u32_e32 v16, v16, v11
	v_add_u32_e32 v16, v16, v12
	v_add_u32_e32 v16, v16, v13
	v_add_u32_e32 v16, v16, v14
	v_add_u32_e32 v16, v16, v15
	v_cmp_ne_u32_e32 vcc, s58, v16
	s_and_saveexec_b64 s[18:19], vcc
	s_cbranch_execz .LBB0_212
	s_and_b32 s22, s28, 0xff
	s_mov_b64 s[20:21], -1
	s_cmp_eq_u32 s22, 0
	s_mov_b64 s[24:25], -1
	s_mov_b64 s[22:23], -1
	s_sleep 1
	s_cbranch_scc1 .LBB0_216
	s_and_saveexec_b64 s[26:27], s[24:25]
	s_cbranch_execz .LBB0_211
	s_branch .LBB0_219
